# diff-attention far-tile skip bounds computed lane-parallel (one load round trip) instead of 64 serialized scalar iterations per unit
# speedup vs baseline: 1.0766x; 1.0436x over previous
; template <int MODE>
; DI void attn_unit(char* lds, const Params& p, int layer, int u) {
;     ...
;   if (MODE == 0) {
;     const float sl2 = exp2f(-(float)(2 * h + 1)) * LOG2E;
;     const unsigned* km = p.nmax + ((b * 4 + h) * 2) * 64; const unsigned* qm = p.nmax + 4096 + ((b * 4 + h) * 2) * 32 + (q0 >> 7);
;     const float q0n = 1.02f * sqrtf(__uint_as_float(qm[0])), q1n = 1.02f * sqrtf(__uint_as_float(qm[32]));
;     const int td = q0 >> 6;
;     const float kd0 = sqrtf(fmaxf(__uint_as_float(km[td]), __uint_as_float(km[td + 1]))), kd1 = sqrtf(fmaxf(__uint_as_float(km[64 + td]), __uint_as_float(km[64 + td + 1])));
;     const float thr0 = -q0n * kd0 - 40.f, thr1 = -q1n * kd1 - 40.f;
;     int lo = td, hi = td + 1;
;     for (int T = 0; T < 64; ++T) {
;       const int dmin = (T < td) ? (q0 - (64 * T + 63)) : ((T > td + 1) ? (64 * T - (q0 + 127)) : 0);
;       const float pen = sl2 * (float)dmin;
;       const bool need = (q0n * sqrtf(__uint_as_float(km[T])) - pen >= thr0) || (q1n * sqrtf(__uint_as_float(km[64 + T])) - pen >= thr1);
;       if (need) { lo = T < lo ? T : lo; hi = T > hi ? T : hi; }
;     }
;     tlo = __builtin_amdgcn_readfirstlane(lo); NT = __builtin_amdgcn_readfirstlane(hi - lo + 1);
.LBB0_606:
	v_lshlrev_b32_e32 v230, 2, v207
	global_load_dword v231, v230, s[66:67]
	global_load_dword v232, v230, s[66:67] offset:256
	v_lshlrev_b32_e32 v233, 6, v207
	v_sub_u32_e32 v234, s4, v233
	v_add_u32_e32 v234, 0xffffffc1, v234
	v_subrev_u32_e32 v235, s4, v233
	v_add_u32_e32 v235, 0xffffff81, v235
	v_cmp_gt_u32_e64 s[0:1], s51, v207
	v_cmp_lt_u32_e64 s[68:69], s56, v207
	s_nop 1
	v_cndmask_b32_e64 v235, 0, v235, s[68:69]
	v_cndmask_b32_e64 v234, v235, v234, s[0:1]
	v_cvt_f32_i32_e32 v234, v234
	v_mul_f32_e32 v234, v119, v234
	s_waitcnt vmcnt(0)
	v_cmp_gt_f32_e32 vcc, s75, v231
	v_mul_f32_e32 v236, 0x4f800000, v231
	s_nop 0
	v_cndmask_b32_e32 v231, v231, v236, vcc
	v_sqrt_f32_e32 v236, v231
	s_nop 0
	v_add_u32_e32 v237, -1, v236
	v_fma_f32 v238, -v237, v236, v231
	v_cmp_ge_f32_e64 s[70:71], 0, v238
	v_add_u32_e32 v238, 1, v236
	s_nop 0
	v_cndmask_b32_e64 v237, v236, v237, s[70:71]
	v_fma_f32 v236, -v238, v236, v231
	v_cmp_lt_f32_e64 s[70:71], 0, v236
	s_nop 1
	v_cndmask_b32_e64 v236, v237, v238, s[70:71]
	v_mul_f32_e32 v237, 0x37800000, v236
	v_cndmask_b32_e32 v236, v236, v237, vcc
	v_cmp_class_f32_e32 vcc, v231, v167
	s_nop 1
	v_cndmask_b32_e32 v231, v236, v231, vcc
	v_cmp_gt_f32_e32 vcc, s75, v232
	v_mul_f32_e32 v236, 0x4f800000, v232
	s_nop 0
	v_cndmask_b32_e32 v232, v232, v236, vcc
	v_sqrt_f32_e32 v236, v232
	s_nop 0
	v_add_u32_e32 v237, -1, v236
	v_fma_f32 v238, -v237, v236, v232
	v_cmp_ge_f32_e64 s[70:71], 0, v238
	v_add_u32_e32 v238, 1, v236
	s_nop 0
	v_cndmask_b32_e64 v237, v236, v237, s[70:71]
	v_fma_f32 v236, -v238, v236, v232
	v_cmp_lt_f32_e64 s[70:71], 0, v236
	s_nop 1
	v_cndmask_b32_e64 v236, v237, v238, s[70:71]
	v_mul_f32_e32 v237, 0x37800000, v236
	v_cndmask_b32_e32 v236, v236, v237, vcc
	v_cmp_class_f32_e32 vcc, v232, v167
	s_nop 1
	v_cndmask_b32_e32 v232, v236, v232, vcc
	v_mul_f32_e32 v231, v118, v231
	v_sub_f32_e32 v231, v231, v234
	v_cmp_ge_f32_e64 s[0:1], v231, v3
	v_fma_f32 v232, v2, v232, -v234
	v_cmp_ge_f32_e64 s[68:69], v232, v4
	s_nop 3
	s_or_b64 s[0:1], s[0:1], s[68:69]
	s_and_b64 s[0:1], s[0:1], exec
	s_cmp_eq_u64 s[0:1], 0
	s_cbranch_scc1 .Lskipdone_d0
	s_ff1_i32_b64 s68, s[0:1]
	s_min_i32 s55, s68, s55
	s_flbit_i32_b64 s68, s[0:1]
	s_sub_i32 s68, 63, s68
	s_max_i32 s52, s68, s52
; template <int MODE>
; DI void attn_unit(char* lds, const Params& p, int layer, int u) {
;     ...
;     tlo = __builtin_amdgcn_readfirstlane(lo); NT = __builtin_amdgcn_readfirstlane(hi - lo + 1);
;   }
;   bf16x8 qf[NKS];
;   if constexpr (MODE == 0) { const bf16_t* q = p.proj + (size_t)token * LDP + C_AQ + h * 64 + comp * 32 + lh * 8;
; #pragma unroll
;     for (int ks = 0; ks < NKS; ++ks) qf[ks] = *(const bf16x8*)(q + ks * 16); }
;   else if constexpr (MODE == 1) { const bf16_t* q = p.qb + (size_t)token * 384 + lh * 8;
; #pragma unroll
;     for (int ks = 0; ks < 4; ++ks) qf[ks] = *(const bf16x8*)(q + h * 64 + ks * 16);
; #pragma unroll
;     for (int ks = 4; ks < 6; ++ks) qf[ks] = *(const bf16x8*)(q + 256 + h * 32 + (ks - 4) * 16); }
;   else { const bf16_t* q = p.proj + (size_t)token * LDP + (MODE == 2 ? C_CQ : C_DQ) + h * 64 + lh * 8;
; #pragma unroll
;     for (int ks = 0; ks < NKS; ++ks) qf[ks] = *(const bf16x8*)(q + ks * 16); }
;   const bf16_t* vtbase = (MODE == 0) ? p.vta + (size_t)((b * 4 + h) * 64) * 4096 : (MODE == 1) ? p.vtb + (size_t)((b * 4 + h) * 64) * 4096 : p.vtc + (size_t)((b * 2 + (h >> 1)) * 64) * 4096;
;   float slope2 = 0.f;
;   if (MODE == 0) slope2 = exp2f(-(float)(2 * h + 1)) * LOG2E;
;   if (MODE == 3) slope2 = exp2f(-(float)(2 * h + 2)) * LOG2E * (float)dl;
;   const int srow = tid >> 3, sc = tid & 7;
;   u32x4 kr0, kr2, vr0;
;   kr2 = (u32x4){0u, 0u, 0u, 0u};
;   auto prefetch = [&](int t) __attribute__((always_inline)) {
;     const int key0 = (MODE == 3) ? q0 - 64 + 64 * t : 64 * (tlo + t);
;     if (MODE != 3) {
;       const size_t tokk = (size_t)(b * SEQ + key0 + srow);
;       const bf16_t* kp = (MODE == 0) ? p.proj + tokk * LDP + C_AK + h * 64 : (MODE == 1) ? p.knb + tokk * 256 + h * 64 : p.proj + tokk * LDP + C_CK + (h >> 1) * 64;
;       kr0 = *(const u32x4*)(kp + sc * 8);
;       if (MODE == 1) kr2 = *(const u32x4*)(p.proj + tokk * LDP + C_BKR + (sc & 3) * 8);
;       vr0 = *(const u32x4*)(vtbase + (size_t)srow * 4096 + key0 + sc * 8);
;     } else {
;       int v = key0 + srow; v = v < 0 ? 0 : (v >= L ? L - 1 : v);
;       const bf16_t* kp = p.proj + (size_t)(b * SEQ + rho + dl * v) * LDP + h * 64;
;       kr0 = *(const u32x4*)(kp + C_DK + sc * 8);
;       vr0 = *(const u32x4*)(kp + C_DV + sc * 8);
;     }
;   };
;   auto stage = [&](char* buf) __attribute__((always_inline)) {
;     char* kd = buf + srow * KST + sc * 16;
.Lskipdone_d0:
.LBB0_620:
	v_bfe_u32 v173, v172, 6, 2
	v_lshlrev_b32_e32 v34, 5, v173
	v_readlane_b32 s56, v252, 0
	v_or_b32_e32 v175, s4, v34
	v_and_b32_e32 v35, 31, v172
	s_lshl_b32 s53, s97, 12
	v_readlane_b32 s64, v252, 8
	v_readlane_b32 s65, v252, 9
	v_or3_b32 v117, v175, v35, s53
	v_ashrrev_i32_e32 v174, 8, v172
	v_mov_b64_e32 v[8:9], s[64:65]
	v_mad_u64_u32 v[0:1], s[0:1], v117, s72, v[8:9]
	s_lshl_b32 s0, s50, 6
	s_lshl_b32 s50, s97, 8
	s_add_i32 s50, s50, s0
	v_readlane_b32 s66, v252, 10
	v_readlane_b32 s67, v252, 11
	s_ashr_i32 s1, s0, 31
	s_ashr_i32 s51, s50, 31
	s_sub_i32 s33, s52, s55
	v_readlane_b32 s70, v252, 14
	s_lshl_b64 s[66:67], s[0:1], 1
	v_lshlrev_b32_e32 v2, 5, v174
	s_lshl_b64 s[50:51], s[50:51], 13
	v_bfe_u32 v36, v172, 5, 1
	v_readlane_b32 s68, v252, 12
	v_readlane_b32 s71, v252, 15
	v_lshl_add_u64 v[0:1], v[0:1], 0, s[66:67]
	v_ashrrev_i32_e32 v3, 31, v2
	v_ashrrev_i32_e32 v10, 3, v172
	s_add_u32 s50, s70, s50
	v_lshl_add_u64 v[0:1], v[2:3], 1, v[0:1]
	v_lshlrev_b32_e32 v112, 4, v36
	s_addc_u32 s51, s71, s51
	s_lshl_b32 s68, s55, 6
	v_add_u32_e32 v176, s53, v10
	v_lshl_add_u64 v[0:1], v[0:1], 0, v[112:113]
	v_add_u32_e32 v16, s68, v176
	v_ashrrev_i32_e32 v11, 31, v10
	v_readlane_b32 s69, v252, 13
	global_load_dwordx4 v[96:99], v[0:1], off
	global_load_dwordx4 v[100:103], v[0:1], off offset:32
	v_and_b32_e32 v37, 7, v172
	v_mad_i64_i32 v[0:1], s[52:53], v16, s72, v[8:9]
	v_lshlrev_b64 v[4:5], 13, v[10:11]
	v_lshl_add_u64 v[0:1], v[0:1], 0, s[66:67]
	v_lshlrev_b32_e32 v12, 4, v37
	v_mov_b32_e32 v13, v113
	v_lshl_add_u64 v[32:33], s[50:51], 0, v[4:5]
	s_ashr_i32 s69, s68, 31
	v_lshl_add_u64 v[0:1], v[0:1], 0, v[12:13]
	v_lshl_add_u64 v[4:5], s[68:69], 1, v[32:33]
	global_load_dwordx4 v[0:3], v[0:1], off offset:512
	v_lshl_add_u64 v[14:15], v[4:5], 0, v[12:13]
	global_load_dwordx4 v[4:7], v[14:15], off
	v_mad_u64_u32 v[120:121], s[50:51], v10, s73, v[12:13]
	s_barrier
	v_lshlrev_b32_e32 v116, 3, v36
	s_cmp_gt_i32 s33, -1
	v_mov_b32_e32 v11, 0
	v_mov_b32_e32 v10, 0
	v_mov_b32_e32 v31, 0
	v_mov_b32_e32 v30, 0
	v_mov_b32_e32 v29, 0
	v_mov_b32_e32 v28, 0
	v_mov_b32_e32 v27, 0
	v_mov_b32_e32 v26, 0
	v_mov_b32_e32 v25, 0
	v_mov_b32_e32 v24, 0
	v_mov_b32_e32 v23, 0
	v_mov_b32_e32 v22, 0
	v_mov_b32_e32 v21, 0
	v_mov_b32_e32 v20, 0
	v_mov_b32_e32 v19, 0
	v_mov_b32_e32 v18, 0
	v_mov_b32_e32 v17, 0
	v_mov_b32_e32 v121, 0
	v_readlane_b32 s57, v252, 1
	v_readlane_b32 s58, v252, 2
	v_readlane_b32 s59, v252, 3
	v_readlane_b32 s60, v252, 4
	v_readlane_b32 s61, v252, 5
	v_readlane_b32 s62, v252, 6
	v_readlane_b32 s63, v252, 7
	s_waitcnt vmcnt(1)
	ds_write_b128 v120, v[0:3]
	s_waitcnt vmcnt(0)
	ds_write_b128 v120, v[4:7] offset:9216
	v_add_u32_e32 v0, 64, v16
	v_mad_i64_i32 v[0:1], s[50:51], v0, s72, v[8:9]
	v_lshl_add_u64 v[0:1], v[0:1], 0, s[66:67]
	v_lshl_add_u64 v[0:1], v[0:1], 0, v[12:13]
	global_load_dwordx4 v[104:107], v[0:1], off offset:512
	global_load_dwordx4 v[108:111], v[14:15], off offset:128
	v_mov_b32_e32 v15, 0
	v_mov_b32_e32 v14, 0
	v_mov_b32_e32 v13, 0
	v_mov_b32_e32 v12, 0
	v_mov_b32_e32 v9, 0
	v_mov_b32_e32 v8, 0
	v_mov_b32_e32 v7, 0
	v_mov_b32_e32 v6, 0
	v_mov_b32_e32 v5, 0
	v_mov_b32_e32 v4, 0
	v_mov_b32_e32 v3, 0
	v_mov_b32_e32 v2, 0
	v_mov_b32_e32 v1, 0
	v_mov_b32_e32 v0, 0
	v_mov_b32_e32 v16, 0
	s_waitcnt lgkmcnt(0)
	s_barrier
	s_cbranch_scc0 .LBB0_636
	s_mov_b32 s36, 0x42680000
	s_mov_b32 s37, 0x426c0000
	v_readlane_b32 s76, v252, 0
	v_pk_mul_f32 v[138:139], v[118:119], s[36:37] op_sel:[1,0]
	s_mov_b32 s36, 0x42600000
	v_readlane_b32 s84, v252, 8
	v_lshlrev_b32_e32 v0, 3, v37
	s_mov_b32 s37, 0x42640000
	v_readlane_b32 s85, v252, 9
	s_add_u32 s52, s84, s66
	v_pk_mul_f32 v[140:141], v[118:119], s[36:37] op_sel:[1,0]
	s_mov_b32 s36, 0x42480000
	v_lshlrev_b32_e32 v0, 1, v0
	v_mov_b32_e32 v1, v113
	v_lshlrev_b32_e32 v2, 2, v36
	s_addc_u32 s53, s85, s67
	s_mov_b32 s37, 0x424c0000
	v_lshl_add_u64 v[154:155], v[32:33], 0, v[0:1]
	v_lshl_add_u64 v[160:161], s[52:53], 0, v[0:1]
	v_sub_u32_e32 v0, v2, v35
	v_pk_mul_f32 v[142:143], v[118:119], s[36:37] op_sel:[1,0]
	s_mov_b32 s36, 0x42400000
	v_sub_u32_e32 v0, v0, v34
	v_mov_b32_e32 v14, v113
	v_mov_b32_e32 v15, v113
	s_mov_b32 s37, 0x42440000
	v_xor_b32_e32 v156, 0x80000000, v119
	v_subrev_u32_e32 v179, s4, v0
	v_mov_b32_e32 v0, v113
	v_mov_b32_e32 v2, v113
	v_mov_b32_e32 v3, v113
	v_mov_b32_e32 v4, v113
	v_mov_b32_e32 v5, v113
	v_mov_b32_e32 v6, v113
	v_mov_b32_e32 v7, v113
	v_mov_b32_e32 v8, v113
	v_mov_b32_e32 v9, v113
	v_mov_b32_e32 v10, v113
	v_mov_b32_e32 v11, v113
	v_mov_b32_e32 v12, v113
	v_mov_b32_e32 v13, v113
	v_mov_b64_e32 v[30:31], v[14:15]
	s_mov_b32 s51, 0
	v_mul_f32_e32 v122, 0, v119
	v_pk_mul_f32 v[124:125], v[118:119], s[12:13] op_sel:[1,0]
	v_pk_mul_f32 v[126:127], v[118:119], s[6:7] op_sel:[1,0]
	v_pk_mul_f32 v[128:129], v[118:119], s[14:15] op_sel:[1,0]
	v_pk_mul_f32 v[130:131], v[118:119], s[34:35] op_sel:[1,0]
	v_pk_mul_f32 v[132:133], v[118:119], s[44:45] op_sel:[1,0]
	v_pk_mul_f32 v[134:135], v[118:119], s[46:47] op_sel:[1,0]
	v_pk_mul_f32 v[136:137], v[118:119], s[48:49] op_sel:[1,0]
	v_mov_b32_e32 v123, v119
	v_pk_mul_f32 v[144:145], v[118:119], s[36:37] op_sel:[1,0]
	v_pk_mul_f32 v[146:147], v[118:119], s[16:17] op_sel:[1,0]
	v_pk_mul_f32 v[148:149], v[118:119], s[18:19] op_sel:[1,0]
	v_pk_mul_f32 v[150:151], v[118:119], s[20:21] op_sel:[1,0]
	v_pk_mul_f32 v[152:153], v[118:119], s[22:23] op_sel:[1,0]
	v_mul_u32_u24_e32 v118, 0x90, v35
	v_lshlrev_b32_e32 v177, 6, v174
	v_or_b32_e32 v178, 31, v175
	v_mov_b32_e32 v158, v156
	v_mov_b32_e32 v159, v156
	s_add_i32 s66, s68, 0x80
	s_add_i32 s50, s33, 1
	v_mov_b32_e32 v163, 0xf149f2ca
	v_mov_b32_e32 v121, 0
	v_mov_b64_e32 v[28:29], v[12:13]
	v_mov_b64_e32 v[26:27], v[10:11]
	v_mov_b64_e32 v[24:25], v[8:9]
	v_mov_b64_e32 v[22:23], v[6:7]
	v_mov_b64_e32 v[20:21], v[4:5]
	v_mov_b64_e32 v[18:19], v[2:3]
	v_mov_b64_e32 v[16:17], v[0:1]
	v_readlane_b32 s77, v252, 1
	v_readlane_b32 s78, v252, 2
	v_readlane_b32 s79, v252, 3
	v_readlane_b32 s80, v252, 4
	v_readlane_b32 s81, v252, 5
	v_readlane_b32 s82, v252, 6
	v_readlane_b32 s83, v252, 7
	v_readlane_b32 s86, v252, 10
	v_readlane_b32 s87, v252, 11
	v_readlane_b32 s88, v252, 12
	v_readlane_b32 s89, v252, 13
	v_readlane_b32 s90, v252, 14
	v_readlane_b32 s91, v252, 15
	s_add_i32 s4, s51, 1
	s_cmp_ge_i32 s51, s33
	s_cbranch_scc1 .LBB0_624

; template <int MODE>
; DI void attn_unit(char* lds, const Params& p, int layer, int u) {
;     ...
;     const int td = q0 >> 6;
;     const float kd0 = sqrtf(fmaxf(__uint_as_float(km[td]), __uint_as_float(km[td + 1]))), kd1 = sqrtf(fmaxf(__uint_as_float(km[64 + td]), __uint_as_float(km[64 + td + 1])));
;     const float thr0 = -q0n * kd0 - 40.f, thr1 = -q1n * kd1 - 40.f;
;     int lo = td, hi = td + 1;
;     for (int T = 0; T < 64; ++T) {
;       const int dmin = (T < td) ? (q0 - (64 * T + 63)) : ((T > td + 1) ? (64 * T - (q0 + 127)) : 0);
;       const float pen = sl2 * (float)dmin;
;       const bool need = (q0n * sqrtf(__uint_as_float(km[T])) - pen >= thr0) || (q1n * sqrtf(__uint_as_float(km[64 + T])) - pen >= thr1);
;       if (need) { lo = T < lo ? T : lo; hi = T > hi ? T : hi; }
;     }
;     tlo = __builtin_amdgcn_readfirstlane(lo); NT = __builtin_amdgcn_readfirstlane(hi - lo + 1);
.LBB0_1583:
	v_lshlrev_b32_e32 v230, 2, v207
	global_load_dword v231, v230, s[66:67]
	global_load_dword v232, v230, s[66:67] offset:256
	v_lshlrev_b32_e32 v233, 6, v207
	v_sub_u32_e32 v234, s4, v233
	v_add_u32_e32 v234, 0xffffffc1, v234
	v_subrev_u32_e32 v235, s4, v233
	v_add_u32_e32 v235, 0xffffff81, v235
	v_cmp_gt_u32_e64 s[0:1], s97, v207
	v_cmp_lt_u32_e64 s[68:69], s54, v207
	s_nop 1
	v_cndmask_b32_e64 v235, 0, v235, s[68:69]
	v_cndmask_b32_e64 v234, v235, v234, s[0:1]
	v_cvt_f32_i32_e32 v234, v234
	v_mul_f32_e32 v234, v119, v234
	s_waitcnt vmcnt(0)
	v_cmp_gt_f32_e32 vcc, s75, v231
	v_mul_f32_e32 v236, 0x4f800000, v231
	s_nop 0
	v_cndmask_b32_e32 v231, v231, v236, vcc
	v_sqrt_f32_e32 v236, v231
	s_nop 0
	v_add_u32_e32 v237, -1, v236
	v_fma_f32 v238, -v237, v236, v231
	v_cmp_ge_f32_e64 s[70:71], 0, v238
	v_add_u32_e32 v238, 1, v236
	s_nop 0
	v_cndmask_b32_e64 v237, v236, v237, s[70:71]
	v_fma_f32 v236, -v238, v236, v231
	v_cmp_lt_f32_e64 s[70:71], 0, v236
	s_nop 1
	v_cndmask_b32_e64 v236, v237, v238, s[70:71]
	v_mul_f32_e32 v237, 0x37800000, v236
	v_cndmask_b32_e32 v236, v236, v237, vcc
	v_cmp_class_f32_e32 vcc, v231, v167
	s_nop 1
	v_cndmask_b32_e32 v231, v236, v231, vcc
	v_cmp_gt_f32_e32 vcc, s75, v232
	v_mul_f32_e32 v236, 0x4f800000, v232
	s_nop 0
	v_cndmask_b32_e32 v232, v232, v236, vcc
	v_sqrt_f32_e32 v236, v232
	s_nop 0
	v_add_u32_e32 v237, -1, v236
	v_fma_f32 v238, -v237, v236, v232
	v_cmp_ge_f32_e64 s[70:71], 0, v238
	v_add_u32_e32 v238, 1, v236
	s_nop 0
	v_cndmask_b32_e64 v237, v236, v237, s[70:71]
	v_fma_f32 v236, -v238, v236, v232
	v_cmp_lt_f32_e64 s[70:71], 0, v236
	s_nop 1
	v_cndmask_b32_e64 v236, v237, v238, s[70:71]
	v_mul_f32_e32 v237, 0x37800000, v236
	v_cndmask_b32_e32 v236, v236, v237, vcc
	v_cmp_class_f32_e32 vcc, v232, v167
	s_nop 1
	v_cndmask_b32_e32 v232, v236, v232, vcc
	v_mul_f32_e32 v231, v118, v231
	v_sub_f32_e32 v231, v231, v234
	v_cmp_ge_f32_e64 s[0:1], v231, v3
	v_fma_f32 v232, v2, v232, -v234
	v_cmp_ge_f32_e64 s[68:69], v232, v4
	s_nop 3
	s_or_b64 s[0:1], s[0:1], s[68:69]
	s_and_b64 s[0:1], s[0:1], exec
	s_cmp_eq_u64 s[0:1], 0
	s_cbranch_scc1 .Lskipdone_d1
	s_ff1_i32_b64 s68, s[0:1]
	s_min_i32 s53, s68, s53
	s_flbit_i32_b64 s68, s[0:1]
	s_sub_i32 s68, 63, s68
	s_max_i32 s50, s68, s50
; template <int MODE>
; DI void attn_unit(char* lds, const Params& p, int layer, int u) {
;     ...
;     for (int T = 0; T < 64; ++T) {
;       const int dmin = (T < td) ? (q0 - (64 * T + 63)) : ((T > td + 1) ? (64 * T - (q0 + 127)) : 0);
;       const float pen = sl2 * (float)dmin;
;       const bool need = (q0n * sqrtf(__uint_as_float(km[T])) - pen >= thr0) || (q1n * sqrtf(__uint_as_float(km[64 + T])) - pen >= thr1);
;       if (need) { lo = T < lo ? T : lo; hi = T > hi ? T : hi; }
;     }
;     tlo = __builtin_amdgcn_readfirstlane(lo); NT = __builtin_amdgcn_readfirstlane(hi - lo + 1);
;     ...
;   if constexpr (MODE == 0) { const bf16_t* q = p.proj + (size_t)token * LDP + C_AQ + h * 64 + comp * 32 + lh * 8;
; #pragma unroll
;     for (int ks = 0; ks < NKS; ++ks) qf[ks] = *(const bf16x8*)(q + ks * 16); }
;   else if constexpr (MODE == 1) { const bf16_t* q = p.qb + (size_t)token * 384 + lh * 8;
; #pragma unroll
;     for (int ks = 0; ks < 4; ++ks) qf[ks] = *(const bf16x8*)(q + h * 64 + ks * 16);
; #pragma unroll
;     for (int ks = 4; ks < 6; ++ks) qf[ks] = *(const bf16x8*)(q + 256 + h * 32 + (ks - 4) * 16); }
;   else { const bf16_t* q = p.proj + (size_t)token * LDP + (MODE == 2 ? C_CQ : C_DQ) + h * 64 + lh * 8;
; #pragma unroll
;     for (int ks = 0; ks < NKS; ++ks) qf[ks] = *(const bf16x8*)(q + ks * 16); }
;   const bf16_t* vtbase = (MODE == 0) ? p.vta + (size_t)((b * 4 + h) * 64) * 4096 : (MODE == 1) ? p.vtb + (size_t)((b * 4 + h) * 64) * 4096 : p.vtc + (size_t)((b * 2 + (h >> 1)) * 64) * 4096;
;   float slope2 = 0.f;
;   if (MODE == 0) slope2 = exp2f(-(float)(2 * h + 1)) * LOG2E;
;   if (MODE == 3) slope2 = exp2f(-(float)(2 * h + 2)) * LOG2E * (float)dl;
;   const int srow = tid >> 3, sc = tid & 7;
;   u32x4 kr0, kr2, vr0;
;   kr2 = (u32x4){0u, 0u, 0u, 0u};
;   auto prefetch = [&](int t) __attribute__((always_inline)) {
;     const int key0 = (MODE == 3) ? q0 - 64 + 64 * t : 64 * (tlo + t);
;     if (MODE != 3) {
;       const size_t tokk = (size_t)(b * SEQ + key0 + srow);
;       const bf16_t* kp = (MODE == 0) ? p.proj + tokk * LDP + C_AK + h * 64 : (MODE == 1) ? p.knb + tokk * 256 + h * 64 : p.proj + tokk * LDP + C_CK + (h >> 1) * 64;
;       kr0 = *(const u32x4*)(kp + sc * 8);
;       if (MODE == 1) kr2 = *(const u32x4*)(p.proj + tokk * LDP + C_BKR + (sc & 3) * 8);
;       vr0 = *(const u32x4*)(vtbase + (size_t)srow * 4096 + key0 + sc * 8);
;     } else {
.Lskipdone_d1:
.LBB0_1597:
	v_bfe_u32 v173, v172, 6, 2
	v_lshlrev_b32_e32 v34, 5, v173
	v_readlane_b32 s56, v252, 0
	v_or_b32_e32 v175, s4, v34
	v_and_b32_e32 v35, 31, v172
	s_lshl_b32 s52, s91, 12
	v_readlane_b32 s64, v252, 8
	v_readlane_b32 s65, v252, 9
	v_or3_b32 v117, v175, v35, s52
	s_sub_i32 s33, s50, s53
	v_mov_b64_e32 v[8:9], s[64:65]
	v_mad_u64_u32 v[0:1], s[0:1], v117, s72, v[8:9]
	s_lshl_b32 s0, s96, 6
	s_lshl_b32 s50, s91, 8
	s_add_i32 s50, s50, s0
	v_ashrrev_i32_e32 v174, 8, v172
	v_readlane_b32 s66, v252, 10
	v_readlane_b32 s67, v252, 11
	s_ashr_i32 s1, s0, 31
	s_ashr_i32 s51, s50, 31
	v_readlane_b32 s70, v252, 14
	s_lshl_b64 s[66:67], s[0:1], 1
	v_lshlrev_b32_e32 v2, 5, v174
	s_lshl_b64 s[50:51], s[50:51], 13
	v_bfe_u32 v36, v172, 5, 1
	v_readlane_b32 s68, v252, 12
	v_readlane_b32 s71, v252, 15
	v_lshl_add_u64 v[0:1], v[0:1], 0, s[66:67]
	v_ashrrev_i32_e32 v3, 31, v2
	v_ashrrev_i32_e32 v10, 3, v172
	s_add_u32 s50, s70, s50
	v_lshl_add_u64 v[0:1], v[2:3], 1, v[0:1]
	v_lshlrev_b32_e32 v112, 4, v36
	s_addc_u32 s51, s71, s51
	s_lshl_b32 s68, s53, 6
	v_add_u32_e32 v176, s52, v10
	v_lshl_add_u64 v[0:1], v[0:1], 0, v[112:113]
	v_add_u32_e32 v16, s68, v176
	v_ashrrev_i32_e32 v11, 31, v10
	v_readlane_b32 s69, v252, 13
	global_load_dwordx4 v[96:99], v[0:1], off
	global_load_dwordx4 v[100:103], v[0:1], off offset:32
	v_and_b32_e32 v37, 7, v172
	v_mad_i64_i32 v[0:1], s[52:53], v16, s72, v[8:9]
	v_lshlrev_b64 v[4:5], 13, v[10:11]
	v_lshl_add_u64 v[0:1], v[0:1], 0, s[66:67]
	v_lshlrev_b32_e32 v12, 4, v37
	v_mov_b32_e32 v13, v113
	v_lshl_add_u64 v[32:33], s[50:51], 0, v[4:5]
	s_ashr_i32 s69, s68, 31
	v_lshl_add_u64 v[0:1], v[0:1], 0, v[12:13]
	v_lshl_add_u64 v[4:5], s[68:69], 1, v[32:33]
	global_load_dwordx4 v[0:3], v[0:1], off offset:512
	v_lshl_add_u64 v[14:15], v[4:5], 0, v[12:13]
	global_load_dwordx4 v[4:7], v[14:15], off
	v_mad_u64_u32 v[120:121], s[50:51], v10, s73, v[12:13]
	s_barrier
	v_lshlrev_b32_e32 v116, 3, v36
	s_cmp_gt_i32 s33, -1
	v_mov_b32_e32 v11, 0
	v_mov_b32_e32 v10, 0
	v_mov_b32_e32 v31, 0
	v_mov_b32_e32 v30, 0
	v_mov_b32_e32 v29, 0
	v_mov_b32_e32 v28, 0
	v_mov_b32_e32 v27, 0
	v_mov_b32_e32 v26, 0
	v_mov_b32_e32 v25, 0
	v_mov_b32_e32 v24, 0
	v_mov_b32_e32 v23, 0
	v_mov_b32_e32 v22, 0
	v_mov_b32_e32 v21, 0
	v_mov_b32_e32 v20, 0
	v_mov_b32_e32 v19, 0
	v_mov_b32_e32 v18, 0
	v_mov_b32_e32 v17, 0
	v_mov_b32_e32 v121, 0
	v_readlane_b32 s57, v252, 1
	v_readlane_b32 s58, v252, 2
	v_readlane_b32 s59, v252, 3
	v_readlane_b32 s60, v252, 4
	v_readlane_b32 s61, v252, 5
	v_readlane_b32 s62, v252, 6
	v_readlane_b32 s63, v252, 7
	s_waitcnt vmcnt(1)
	ds_write_b128 v120, v[0:3]
	s_waitcnt vmcnt(0)
	ds_write_b128 v120, v[4:7] offset:9216
	v_add_u32_e32 v0, 64, v16
	v_mad_i64_i32 v[0:1], s[50:51], v0, s72, v[8:9]
	v_lshl_add_u64 v[0:1], v[0:1], 0, s[66:67]
	v_lshl_add_u64 v[0:1], v[0:1], 0, v[12:13]
	global_load_dwordx4 v[104:107], v[0:1], off offset:512
	global_load_dwordx4 v[108:111], v[14:15], off offset:128
	v_mov_b32_e32 v15, 0
	v_mov_b32_e32 v14, 0
	v_mov_b32_e32 v13, 0
	v_mov_b32_e32 v12, 0
	v_mov_b32_e32 v9, 0
	v_mov_b32_e32 v8, 0
	v_mov_b32_e32 v7, 0
	v_mov_b32_e32 v6, 0
	v_mov_b32_e32 v5, 0
	v_mov_b32_e32 v4, 0
	v_mov_b32_e32 v3, 0
	v_mov_b32_e32 v2, 0
	v_mov_b32_e32 v1, 0
	v_mov_b32_e32 v0, 0
	v_mov_b32_e32 v16, 0
	s_waitcnt lgkmcnt(0)
	s_barrier
	s_cbranch_scc0 .LBB0_1613
	s_mov_b32 s8, 0x42480000
	s_mov_b32 s9, 0x424c0000
	v_pk_mul_f32 v[142:143], v[118:119], s[8:9] op_sel:[1,0]
	v_readlane_b32 s8, v252, 0
	v_readlane_b32 s16, v252, 8
	v_lshlrev_b32_e32 v0, 3, v37
	v_readlane_b32 s17, v252, 9
	s_add_u32 s52, s16, s66
	v_lshlrev_b32_e32 v0, 1, v0
	v_mov_b32_e32 v1, v113
	v_lshlrev_b32_e32 v2, 2, v36
	s_addc_u32 s53, s17, s67
	v_lshl_add_u64 v[154:155], v[32:33], 0, v[0:1]
	v_lshl_add_u64 v[160:161], s[52:53], 0, v[0:1]
	v_sub_u32_e32 v0, v2, v35
	v_sub_u32_e32 v0, v0, v34
	v_mov_b32_e32 v14, v113
	v_mov_b32_e32 v15, v113
	v_xor_b32_e32 v156, 0x80000000, v119
	v_subrev_u32_e32 v179, s4, v0
	v_mov_b32_e32 v0, v113
	v_mov_b32_e32 v2, v113
	v_mov_b32_e32 v3, v113
	v_mov_b32_e32 v4, v113
	v_mov_b32_e32 v5, v113
	v_mov_b32_e32 v6, v113
	v_mov_b32_e32 v7, v113
	v_mov_b32_e32 v8, v113
	v_mov_b32_e32 v9, v113
	v_mov_b32_e32 v10, v113
	v_mov_b32_e32 v11, v113
	v_mov_b32_e32 v12, v113
	v_mov_b32_e32 v13, v113
	v_mov_b64_e32 v[30:31], v[14:15]
	s_mov_b32 s50, 0
	v_mul_f32_e32 v122, 0, v119
	v_pk_mul_f32 v[124:125], v[118:119], s[30:31] op_sel:[1,0]
	v_pk_mul_f32 v[126:127], v[118:119], s[6:7] op_sel:[1,0]
	v_pk_mul_f32 v[128:129], v[118:119], s[36:37] op_sel:[1,0]
	v_pk_mul_f32 v[130:131], v[118:119], s[34:35] op_sel:[1,0]
	v_pk_mul_f32 v[132:133], v[118:119], s[44:45] op_sel:[1,0]
	v_pk_mul_f32 v[134:135], v[118:119], s[46:47] op_sel:[1,0]
	v_pk_mul_f32 v[136:137], v[118:119], s[48:49] op_sel:[1,0]
	v_mov_b32_e32 v123, v119
	v_pk_mul_f32 v[138:139], v[118:119], s[86:87] op_sel:[1,0]
	v_pk_mul_f32 v[140:141], v[118:119], s[92:93] op_sel:[1,0]
	v_pk_mul_f32 v[144:145], v[118:119], s[38:39] op_sel:[1,0]
	v_pk_mul_f32 v[146:147], v[118:119], s[40:41] op_sel:[1,0]
	v_pk_mul_f32 v[148:149], v[118:119], s[42:43] op_sel:[1,0]
	v_pk_mul_f32 v[150:151], v[118:119], s[84:85] op_sel:[1,0]
	v_pk_mul_f32 v[152:153], v[118:119], s[24:25] op_sel:[1,0]
	v_mul_u32_u24_e32 v118, 0x90, v35
	v_lshlrev_b32_e32 v177, 6, v174
	v_or_b32_e32 v178, 31, v175
	v_mov_b32_e32 v158, v156
	v_mov_b32_e32 v159, v156
	s_add_i32 s66, s68, 0x80
	s_add_i32 s91, s33, 1
	v_mov_b32_e32 v163, 0xf149f2ca
	v_mov_b32_e32 v121, 0
	v_mov_b64_e32 v[28:29], v[12:13]
	v_mov_b64_e32 v[26:27], v[10:11]
	v_mov_b64_e32 v[24:25], v[8:9]
	v_mov_b64_e32 v[22:23], v[6:7]
	v_mov_b64_e32 v[20:21], v[4:5]
	v_mov_b64_e32 v[18:19], v[2:3]
	v_mov_b64_e32 v[16:17], v[0:1]
	v_readlane_b32 s9, v252, 1
	v_readlane_b32 s10, v252, 2
	v_readlane_b32 s11, v252, 3
	v_readlane_b32 s12, v252, 4
	v_readlane_b32 s13, v252, 5
	v_readlane_b32 s14, v252, 6
	v_readlane_b32 s15, v252, 7
	v_readlane_b32 s18, v252, 10
	v_readlane_b32 s19, v252, 11
	v_readlane_b32 s20, v252, 12
	v_readlane_b32 s21, v252, 13
	v_readlane_b32 s22, v252, 14
	v_readlane_b32 s23, v252, 15
	s_add_i32 s4, s50, 1
	s_cmp_ge_i32 s50, s33
	s_cbranch_scc1 .LBB0_1601
